# diff-attention inner loop rewritten by hand: one symmetric software-pipelined loop for all 8 waves (P.V + next-tile QK^T MFMAs interleaved with own softmax VALU, one barrier per tile) replacing the tw
# speedup vs baseline: 1.0222x; 1.0222x over previous
; __device__ __forceinline__ int opaque_tid(int wv) { int lane_; asm volatile("v_mbcnt_lo_u32_b32 %0, -1, 0\n\tv_mbcnt_hi_u32_b32 %0, -1, %0" : "=v"(lane_)); return wv * 64 + lane_; }
; #define SBAR() __builtin_amdgcn_sched_barrier(0)
; #define STAGE(t) do { const char* kt_ = Pk + (size_t)((t) * KVBLK) * (INC * 2); const int so_ = ((t) & 3) * SHM_K; \
;     GLDS(kt_ + koff, ldsA + 4 * SHM_V + so_); GLDS(kt_ + 32 * INC * 2 + koff, ldsA + 4 * SHM_V + so_ + 8192); \
;     GLDS(kt_ + voff, ldsA + so_); GLDS(kt_ + 32 * INC * 2 + voff, ldsA + so_ + 8192); } while (0)
; #define ENDI() do { asm volatile("s_waitcnt vmcnt(0)" ::: "memory"); __syncthreads(); } while (0)
; #define BIAS(P0, P1, t) bias_init(P0, P1, (float)(iposk - (t) * KVBLK), nslope2, nM2, relw + (t) * KVBLK)
; __device__ __forceinline__ void diff_unit(const DiffArgs& A, int b, int h, int qb, char* lds, int wv) {
;     ...
;     BIAS(pA0, pA1, 0); qkt<4>(pA0, pA1, K_lds, qr, r32, hi, colB0);
;     ...
;     if (c == 0) {
;     ...
;         const int lp_ = opaque_tid(wv) & 63, r32p = lp_ & 31, hip = lp_ >> 5;
;         exp_half(pA0);
;         ENDI();
; #pragma unroll 1
;         for (int j = 1; j + 1 < NT; j += 2) {
;             STAGE(j + 1);
;             SBAR(); BIAS(pB0, pB1, j); qkt<4>(pB0, pB1, K_lds + SLOT(j), qr, r32p, hip, colB0);
;             exp_half(pA1); pack_p(pA0, pA1, l_reg, pa0, pa1, pa2, pa3); SBAR();
;             pv_d0(o, vb0 + SLOT(j - 1), pa0, pa1, pa2, pa3); exp_half(pB0);
.LBB0_225:
	v_and_b32_e32 v0, 63, v3
	v_lshlrev_b32_e32 v3, 4, v0
	v_lshlrev_b32_e32 v1, 3, v0
	v_and_b32_e32 v3, 0xc0, v3
	v_lshlrev_b32_e32 v0, 1, v0
	v_and_or_b32 v3, v1, 24, v3
	v_and_b32_e32 v0, 32, v0
	v_and_b32_e32 v1, 0x100, v1
	s_cmp_lg_u32 0, -1
	v_or3_b32 v0, v3, v0, v1
	s_cselect_b32 s6, 0, 0
	v_add_u32_e32 v252, s6, v0
	v_lshlrev_b32_e32 v0, 4, v2
	v_lshlrev_b32_e32 v9, 8, v2
	v_and_b32_e32 v10, 0xf0, v0
	s_add_i32 s6, 0, 0x10000
	v_or_b32_e32 v8, s52, v4
	v_bitop3_b32 v4, s52, v10, v4 bitop3:0x36
	v_add_u32_e32 v11, s6, v9
	v_add3_u32 v0, s6, v4, v9
	v_add_u32_e32 v4, v11, v4
	ds_read_b128 v[0:3], v0
	ds_read_b128 v[4:7], v4 offset:8192
	s_waitcnt lgkmcnt(0)
	v_mfma_f32_32x32x16_bf16 v[64:79], v[4:7], v[172:175], v[64:79]
	v_bitop3_b32 v4, v8, v10, 32 bitop3:0x36
	s_movk_i32 s7, 0x60
	s_cmpk_lt_u32 s3, 0x100
	v_mov_b32_e32 v189, v177
	s_cselect_b64 s[36:37], -1, 0
	s_cmpk_gt_u32 s3, 0xff
	v_mfma_f32_32x32x16_bf16 v[80:95], v[0:3], v[172:175], v[80:95]
	v_add3_u32 v0, s6, v4, v9
	v_add_u32_e32 v4, v11, v4
	ds_read_b128 v[0:3], v0
	ds_read_b128 v[4:7], v4 offset:8192
	s_waitcnt lgkmcnt(0)
	v_mfma_f32_32x32x16_bf16 v[64:79], v[4:7], v[168:171], v[64:79]
	v_bitop3_b32 v4, v8, v10, 64 bitop3:0x36
	v_mfma_f32_32x32x16_bf16 v[80:95], v[0:3], v[168:171], v[80:95]
	v_add3_u32 v0, s6, v4, v9
	v_add_u32_e32 v4, v11, v4
	ds_read_b128 v[0:3], v0
	ds_read_b128 v[4:7], v4 offset:8192
	s_waitcnt lgkmcnt(0)
	v_mfma_f32_32x32x16_bf16 v[64:79], v[4:7], v[164:167], v[64:79]
	v_bitop3_b32 v4, v8, v10, s7 bitop3:0x36
	v_mfma_f32_32x32x16_bf16 v[80:95], v[0:3], v[164:167], v[80:95]
	v_add3_u32 v0, s6, v4, v9
	v_add_u32_e32 v4, v11, v4
	ds_read_b128 v[0:3], v0
	ds_read_b128 v[4:7], v4 offset:8192
	s_mov_b64 s[6:7], -1
	s_waitcnt lgkmcnt(0)
	v_mfma_f32_32x32x16_bf16 v[80:95], v[0:3], v[160:163], v[80:95]
	v_mfma_f32_32x32x16_bf16 v[64:79], v[4:7], v[160:163], v[64:79]
	s_branch .Lsym_entry
.Lsym_entry:
	v_mov_b32_e32 v0, 0
	v_mov_b32_e32 v1, 0
	v_mov_b32_e32 v2, 0
	v_mov_b32_e32 v3, 0
	v_mov_b32_e32 v4, 0
	v_mov_b32_e32 v5, 0
	v_mov_b32_e32 v6, 0
	v_mov_b32_e32 v7, 0
	v_mov_b32_e32 v8, 0
	v_mov_b32_e32 v9, 0
	v_mov_b32_e32 v10, 0
	v_mov_b32_e32 v11, 0
	v_mov_b32_e32 v12, 0
	v_mov_b32_e32 v13, 0
	v_mov_b32_e32 v14, 0
	v_mov_b32_e32 v15, 0
	v_mov_b32_e32 v16, 0
	v_mov_b32_e32 v17, 0
	v_mov_b32_e32 v18, 0
	v_mov_b32_e32 v19, 0
	v_mov_b32_e32 v20, 0
	v_mov_b32_e32 v21, 0
	v_mov_b32_e32 v22, 0
	v_mov_b32_e32 v23, 0
	v_mov_b32_e32 v24, 0
	v_mov_b32_e32 v25, 0
	v_mov_b32_e32 v26, 0
	v_mov_b32_e32 v27, 0
	v_mov_b32_e32 v28, 0
	v_mov_b32_e32 v29, 0
	v_mov_b32_e32 v30, 0
	v_mov_b32_e32 v31, 0
	v_mov_b32_e32 v32, 0
	v_mov_b32_e32 v33, 0
	v_mov_b32_e32 v34, 0
	v_mov_b32_e32 v35, 0
	v_mov_b32_e32 v36, 0
	v_mov_b32_e32 v37, 0
	v_mov_b32_e32 v38, 0
	v_mov_b32_e32 v39, 0
	v_mov_b32_e32 v40, 0
	v_mov_b32_e32 v41, 0
	v_mov_b32_e32 v42, 0
	v_mov_b32_e32 v43, 0
	v_mov_b32_e32 v44, 0
	v_mov_b32_e32 v45, 0
	v_mov_b32_e32 v46, 0
	v_mov_b32_e32 v47, 0
	v_mov_b32_e32 v48, 0
	v_mov_b32_e32 v49, 0
	v_mov_b32_e32 v50, 0
	v_mov_b32_e32 v51, 0
	v_mov_b32_e32 v52, 0
	v_mov_b32_e32 v53, 0
	v_mov_b32_e32 v54, 0
	v_mov_b32_e32 v55, 0
	v_mov_b32_e32 v56, 0
	v_mov_b32_e32 v57, 0
	v_mov_b32_e32 v58, 0
	v_mov_b32_e32 v59, 0
	v_mov_b32_e32 v60, 0
	v_mov_b32_e32 v61, 0
	v_mov_b32_e32 v62, 0
	v_mov_b32_e32 v63, 0
	v_mov_b32_e32 v182, 0
	v_mbcnt_lo_u32_b32 v190, -1, 0
	v_mbcnt_hi_u32_b32 v190, -1, v190
	v_and_b32_e32 v191, 31, v190
	v_lshrrev_b32_e32 v187, 5, v190
	v_lshlrev_b32_e32 v185, 4, v187
	v_or_b32_e32 v185, s52, v185
	v_and_b32_e32 v183, 15, v191
	v_lshlrev_b32_e32 v183, 4, v183
	v_xor_b32_e32 v185, v185, v183
	v_lshlrev_b32_e32 v183, 8, v191
	v_xor_b32_e32 v178, 0, v185
	v_add_u32_e32 v178, v178, v183
	v_xor_b32_e32 v179, 32, v185
	v_add_u32_e32 v179, v179, v183
	v_xor_b32_e32 v180, 64, v185
	v_add_u32_e32 v180, v180, v183
	v_xor_b32_e32 v181, 96, v185
	v_add_u32_e32 v181, v181, v183
	s_mov_b32 s54, 0
	s_mov_b32 s55, 0
	s_mov_b32 s58, 0x8000
	s_add_u32 s56, s20, 0x1c1e00
	s_addc_u32 s57, s21, 0
	v_exp_f32_e32 v80, v80
	v_exp_f32_e32 v81, v81
	v_exp_f32_e32 v82, v82
	v_exp_f32_e32 v83, v83
	v_add_f32_e32 v182, v80, v182
	v_add_f32_e32 v182, v81, v182
	v_cvt_pk_bf16_f32 v128, v80, v81
	v_exp_f32_e32 v84, v84
	v_exp_f32_e32 v85, v85
	v_add_f32_e32 v182, v82, v182
	v_add_f32_e32 v182, v83, v182
	v_cvt_pk_bf16_f32 v129, v82, v83
	v_exp_f32_e32 v86, v86
	v_exp_f32_e32 v87, v87
	v_add_f32_e32 v182, v84, v182
	v_add_f32_e32 v182, v85, v182
	v_cvt_pk_bf16_f32 v130, v84, v85
	v_add_f32_e32 v182, v86, v182
	v_add_f32_e32 v182, v87, v182
	v_cvt_pk_bf16_f32 v131, v86, v87
.Lsym_loop:
	s_waitcnt vmcnt(0)
	s_barrier
	s_add_i32 s53, s55, 0x4000
	s_and_b32 s53, s53, 0xc000
	s_add_i32 s53, s53, 0x10000
	v_add_u32_e32 v196, s53, v178
	ds_read_b128 v[192:195], v196
	ds_read_b128 v[196:199], v196 offset:8192
	v_add_u32_e32 v204, s53, v179
	ds_read_b128 v[200:203], v204
	ds_read_b128 v[204:207], v204 offset:8192
	v_add_u32_e32 v212, s53, v180
	ds_read_b128 v[208:211], v212
	ds_read_b128 v[212:215], v212 offset:8192
	v_add_u32_e32 v220, s53, v181
	ds_read_b128 v[216:219], v220
	ds_read_b128 v[220:223], v220 offset:8192
	s_add_i32 s53, s54, 2
	s_cmp_le_i32 s53, s62
	s_cbranch_scc0 .Lsym_nostage_e
	s_add_i32 s53, s25, s58
	s_mov_b32 m0, s53
	s_add_u32 s60, s56, 0x70000
	s_addc_u32 s61, s57, 0
	global_load_lds_dwordx4 v176, s[56:57]
	s_add_i32 m0, s53, 0x2000
	s_nop 0
	global_load_lds_dwordx4 v176, s[60:61]
	s_add_i32 s53, s24, s58
	s_mov_b32 m0, s53
	s_nop 0
	global_load_lds_dwordx4 v188, s[56:57]
	s_add_i32 m0, s53, 0x2000
	s_nop 0
	global_load_lds_dwordx4 v188, s[60:61]
	s_add_u32 s56, s56, 0xe0000
	s_addc_u32 s57, s57, 0
	s_add_i32 s58, s58, 0x4000
	s_and_b32 s58, s58, 0xc000
; #define SBAR() __builtin_amdgcn_sched_barrier(0)
; template <int KS> __device__ __forceinline__ void pv_ks(f32x16* o, int vb, bf16x8 pa) {
;     const s16x4 l0 = tr_read<v_rd_off(0, KS, 0)>(vb), h0 = tr_read<v_rd_off(0, KS, 1)>(vb), l1 = tr_read<v_rd_off(1, KS, 0)>(vb), h1 = tr_read<v_rd_off(1, KS, 1)>(vb);
;     const s16x4 l2 = tr_read<v_rd_off(2, KS, 0)>(vb), h2 = tr_read<v_rd_off(2, KS, 1)>(vb), l3 = tr_read<v_rd_off(3, KS, 0)>(vb), h3 = tr_read<v_rd_off(3, KS, 1)>(vb);
;     ...
;     asm volatile("s_waitcnt lgkmcnt(6)" ::: "memory"); SBAR();
;     o[0] = __builtin_amdgcn_mfma_f32_32x32x16_bf16(pa, PK(l0, h0), o[0], 0, 0, 0);
;     asm volatile("s_waitcnt lgkmcnt(4)" ::: "memory"); SBAR();
;     o[1] = __builtin_amdgcn_mfma_f32_32x32x16_bf16(pa, PK(l1, h1), o[1], 0, 0, 0);
;     asm volatile("s_waitcnt lgkmcnt(2)" ::: "memory"); SBAR();
;     o[2] = __builtin_amdgcn_mfma_f32_32x32x16_bf16(pa, PK(l2, h2), o[2], 0, 0, 0);
;     asm volatile("s_waitcnt lgkmcnt(0)" ::: "memory"); SBAR();
;     o[3] = __builtin_amdgcn_mfma_f32_32x32x16_bf16(pa, PK(l3, h3), o[3], 0, 0, 0);
;     ...
; }
; __device__ __forceinline__ void pv_d0(f32x16* o, int vb, bf16x8 pa0, bf16x8 pa1, bf16x8 pa2, bf16x8 pa3) {
;     __builtin_amdgcn_s_setprio(1);
;     pv_ks<0>(o, vb, pa0); pv_ks<1>(o, vb, pa1); pv_ks<2>(o, vb, pa2); pv_ks<3>(o, vb, pa3);
;     __builtin_amdgcn_s_setprio(0);
; }
; __device__ __forceinline__ void bias_init(f32x16& p0, f32x16& p1, float base, float nslope2, float nM2, int rel  ) {
;     if (rel <= -63 || rel >= 31) {
;         const float sg = (rel < 0) ? -nslope2 : nslope2, lbv = fmaf(-sg, base, nM2);
; #pragma unroll
;         for (int r = 0; r < 16; ++r) { p0[r] = fmaf((float)((r & 3) + 8 * (r >> 2)), sg, lbv); p1[r] = fmaf((float)((r & 3) + 8 * (r >> 2) + 32), sg, lbv); }
;     } else {
; #pragma unroll
;         for (int r = 0; r < 16; ++r) { const float d = base - (float)((r & 3) + 8 * (r >> 2));
;             p0[r] = fmaf(fabsf(d), nslope2, nM2); p1[r] = fmaf(fabsf(d - 32.f), nslope2, nM2); }
;     }
; }
.Lsym_nostage_e:
	s_add_i32 s53, s54, 1
	s_lshl_b32 s53, s53, 6
	v_subrev_u32_e32 v183, s53, v236
	v_cvt_f32_i32_e32 v183, v183
	s_add_i32 s53, s53, s63
	s_add_i32 s100, s53, 62
	s_cmp_lt_u32 s100, 93
	s_cbranch_scc1 .Lsym_diag_e
	s_cmp_lt_i32 s53, 0
	s_cselect_b32 s100, -1.0, 1.0
	v_mul_f32_e32 v185, s100, v186
	v_fma_f32 v187, -v185, v183, s16
	v_fmamk_f32 v112, v185, 0x00000000, v187
	v_fmamk_f32 v96, v185, 0x42000000, v187
	v_fmamk_f32 v113, v185, 0x3f800000, v187
	v_fmamk_f32 v97, v185, 0x42040000, v187
	v_fmamk_f32 v114, v185, 0x40000000, v187
	v_fmamk_f32 v98, v185, 0x42080000, v187
	v_fmamk_f32 v115, v185, 0x40400000, v187
	v_fmamk_f32 v99, v185, 0x420c0000, v187
	v_fmamk_f32 v116, v185, 0x41000000, v187
	v_fmamk_f32 v100, v185, 0x42200000, v187
	v_fmamk_f32 v117, v185, 0x41100000, v187
	v_fmamk_f32 v101, v185, 0x42240000, v187
	v_fmamk_f32 v118, v185, 0x41200000, v187
	v_fmamk_f32 v102, v185, 0x42280000, v187
	v_fmamk_f32 v119, v185, 0x41300000, v187
	v_fmamk_f32 v103, v185, 0x422c0000, v187
	v_fmamk_f32 v120, v185, 0x41800000, v187
	v_fmamk_f32 v104, v185, 0x42400000, v187
	v_fmamk_f32 v121, v185, 0x41880000, v187
	v_fmamk_f32 v105, v185, 0x42440000, v187
	v_fmamk_f32 v122, v185, 0x41900000, v187
	v_fmamk_f32 v106, v185, 0x42480000, v187
	v_fmamk_f32 v123, v185, 0x41980000, v187
	v_fmamk_f32 v107, v185, 0x424c0000, v187
	v_fmamk_f32 v124, v185, 0x41c00000, v187
	v_fmamk_f32 v108, v185, 0x42600000, v187
	v_fmamk_f32 v125, v185, 0x41c80000, v187
	v_fmamk_f32 v109, v185, 0x42640000, v187
	v_fmamk_f32 v126, v185, 0x41d00000, v187
	v_fmamk_f32 v110, v185, 0x42680000, v187
	v_fmamk_f32 v127, v185, 0x41d80000, v187
	v_fmamk_f32 v111, v185, 0x426c0000, v187
	s_branch .Lsym_biasdone_e
.Lsym_diag_e:
	v_add_f32_e32 v190, 0x00000000, v183
	v_add_f32_e32 v191, 0xc2000000, v183
	v_fma_f32 v112, |v190|, v186, s16
	v_fma_f32 v96, |v191|, v186, s16
	v_add_f32_e32 v190, 0xbf800000, v183
	v_add_f32_e32 v191, 0xc2040000, v183
	v_fma_f32 v113, |v190|, v186, s16
	v_fma_f32 v97, |v191|, v186, s16
	v_add_f32_e32 v190, 0xc0000000, v183
	v_add_f32_e32 v191, 0xc2080000, v183
	v_fma_f32 v114, |v190|, v186, s16
	v_fma_f32 v98, |v191|, v186, s16
	v_add_f32_e32 v190, 0xc0400000, v183
	v_add_f32_e32 v191, 0xc20c0000, v183
	v_fma_f32 v115, |v190|, v186, s16
	v_fma_f32 v99, |v191|, v186, s16
	v_add_f32_e32 v190, 0xc1000000, v183
	v_add_f32_e32 v191, 0xc2200000, v183
	v_fma_f32 v116, |v190|, v186, s16
	v_fma_f32 v100, |v191|, v186, s16
	v_add_f32_e32 v190, 0xc1100000, v183
	v_add_f32_e32 v191, 0xc2240000, v183
	v_fma_f32 v117, |v190|, v186, s16
	v_fma_f32 v101, |v191|, v186, s16
	v_add_f32_e32 v190, 0xc1200000, v183
	v_add_f32_e32 v191, 0xc2280000, v183
	v_fma_f32 v118, |v190|, v186, s16
	v_fma_f32 v102, |v191|, v186, s16
	v_add_f32_e32 v190, 0xc1300000, v183
	v_add_f32_e32 v191, 0xc22c0000, v183
	v_fma_f32 v119, |v190|, v186, s16
	v_fma_f32 v103, |v191|, v186, s16
	v_add_f32_e32 v190, 0xc1800000, v183
	v_add_f32_e32 v191, 0xc2400000, v183
	v_fma_f32 v120, |v190|, v186, s16
	v_fma_f32 v104, |v191|, v186, s16
	v_add_f32_e32 v190, 0xc1880000, v183
	v_add_f32_e32 v191, 0xc2440000, v183
	v_fma_f32 v121, |v190|, v186, s16
	v_fma_f32 v105, |v191|, v186, s16
	v_add_f32_e32 v190, 0xc1900000, v183
	v_add_f32_e32 v191, 0xc2480000, v183
	v_fma_f32 v122, |v190|, v186, s16
	v_fma_f32 v106, |v191|, v186, s16
	v_add_f32_e32 v190, 0xc1980000, v183
	v_add_f32_e32 v191, 0xc24c0000, v183
	v_fma_f32 v123, |v190|, v186, s16
	v_fma_f32 v107, |v191|, v186, s16
	v_add_f32_e32 v190, 0xc1c00000, v183
	v_add_f32_e32 v191, 0xc2600000, v183
	v_fma_f32 v124, |v190|, v186, s16
	v_fma_f32 v108, |v191|, v186, s16
	v_add_f32_e32 v190, 0xc1c80000, v183
	v_add_f32_e32 v191, 0xc2640000, v183
	v_fma_f32 v125, |v190|, v186, s16
	v_fma_f32 v109, |v191|, v186, s16
	v_add_f32_e32 v190, 0xc1d00000, v183
	v_add_f32_e32 v191, 0xc2680000, v183
	v_fma_f32 v126, |v190|, v186, s16
	v_fma_f32 v110, |v191|, v186, s16
	v_add_f32_e32 v190, 0xc1d80000, v183
	v_add_f32_e32 v191, 0xc26c0000, v183
	v_fma_f32 v127, |v190|, v186, s16
	v_fma_f32 v111, |v191|, v186, s16
.Lsym_biasdone_e:
	v_add_u32_e32 v184, s55, v252
	ds_read_b64_tr_b16 v[144:145], v184 offset:0
	ds_read_b64_tr_b16 v[146:147], v184 offset:2048
	ds_read_b64_tr_b16 v[148:149], v184 offset:512
	ds_read_b64_tr_b16 v[150:151], v184 offset:2560
	ds_read_b64_tr_b16 v[152:153], v184 offset:1024
	ds_read_b64_tr_b16 v[154:155], v184 offset:3072
	ds_read_b64_tr_b16 v[156:157], v184 offset:1536
	ds_read_b64_tr_b16 v[158:159], v184 offset:3584
	s_waitcnt lgkmcnt(6)
	v_mfma_f32_32x32x16_bf16 v[48:63], v[128:131], v[144:147], v[48:63]
	ds_read_b64_tr_b16 v[144:145], v184 offset:4096
	ds_read_b64_tr_b16 v[146:147], v184 offset:6144
	v_exp_f32_e32 v88, v88
	v_exp_f32_e32 v89, v89
	s_waitcnt lgkmcnt(6)
	v_mfma_f32_32x32x16_bf16 v[32:47], v[128:131], v[148:151], v[32:47]
	ds_read_b64_tr_b16 v[148:149], v184 offset:4608
	ds_read_b64_tr_b16 v[150:151], v184 offset:6656
	v_exp_f32_e32 v90, v90
	v_exp_f32_e32 v91, v91
	v_add_f32_e32 v182, v88, v182
	v_add_f32_e32 v182, v89, v182
	v_cvt_pk_bf16_f32 v132, v88, v89
	s_waitcnt lgkmcnt(6)
	v_mfma_f32_32x32x16_bf16 v[16:31], v[128:131], v[152:155], v[16:31]
	ds_read_b64_tr_b16 v[152:153], v184 offset:5120
	ds_read_b64_tr_b16 v[154:155], v184 offset:7168
	v_exp_f32_e32 v92, v92
	v_exp_f32_e32 v93, v93
	v_add_f32_e32 v182, v90, v182
	v_add_f32_e32 v182, v91, v182
	v_cvt_pk_bf16_f32 v133, v90, v91
	s_waitcnt lgkmcnt(6)
; template <int KS> __device__ __forceinline__ void pv_ks(f32x16* o, int vb, bf16x8 pa) {
;     const s16x4 l0 = tr_read<v_rd_off(0, KS, 0)>(vb), h0 = tr_read<v_rd_off(0, KS, 1)>(vb), l1 = tr_read<v_rd_off(1, KS, 0)>(vb), h1 = tr_read<v_rd_off(1, KS, 1)>(vb);
;     const s16x4 l2 = tr_read<v_rd_off(2, KS, 0)>(vb), h2 = tr_read<v_rd_off(2, KS, 1)>(vb), l3 = tr_read<v_rd_off(3, KS, 0)>(vb), h3 = tr_read<v_rd_off(3, KS, 1)>(vb);
;     ...
;     asm volatile("s_waitcnt lgkmcnt(6)" ::: "memory"); SBAR();
;     o[0] = __builtin_amdgcn_mfma_f32_32x32x16_bf16(pa, PK(l0, h0), o[0], 0, 0, 0);
;     asm volatile("s_waitcnt lgkmcnt(4)" ::: "memory"); SBAR();
;     o[1] = __builtin_amdgcn_mfma_f32_32x32x16_bf16(pa, PK(l1, h1), o[1], 0, 0, 0);
;     asm volatile("s_waitcnt lgkmcnt(2)" ::: "memory"); SBAR();
;     o[2] = __builtin_amdgcn_mfma_f32_32x32x16_bf16(pa, PK(l2, h2), o[2], 0, 0, 0);
;     asm volatile("s_waitcnt lgkmcnt(0)" ::: "memory"); SBAR();
;     o[3] = __builtin_amdgcn_mfma_f32_32x32x16_bf16(pa, PK(l3, h3), o[3], 0, 0, 0);
;     ...
; }
; __device__ __forceinline__ void pv_d0(f32x16* o, int vb, bf16x8 pa0, bf16x8 pa1, bf16x8 pa2, bf16x8 pa3) {
;     __builtin_amdgcn_s_setprio(1);
;     pv_ks<0>(o, vb, pa0); pv_ks<1>(o, vb, pa1); pv_ks<2>(o, vb, pa2); pv_ks<3>(o, vb, pa3);
;     __builtin_amdgcn_s_setprio(0);
; }
; __device__ __forceinline__ void exp_half(f32x16& p) {
; #pragma unroll
;     for (int r = 0; r < 16; ++r) p[r] = __builtin_amdgcn_exp2f(p[r]);
; }
; __device__ __forceinline__ void pack_p(const f32x16& p0, const f32x16& p1, float& l_reg, bf16x8& pa0, bf16x8& pa1, bf16x8& pa2, bf16x8& pa3) {
; __device__ __forceinline__ void diff_unit(const DiffArgs& A, int b, int h, int qb, char* lds, int wv) {
;     ...
;         for (int j = 1; j + 1 < NT; j += 2) {
;             STAGE(j + 1);
;             SBAR(); BIAS(pB0, pB1, j); qkt<4>(pB0, pB1, K_lds + SLOT(j), qr, r32p, hip, colB0);
;             exp_half(pA1); pack_p(pA0, pA1, l_reg, pa0, pa1, pa2, pa3); SBAR();
;             pv_d0(o, vb0 + SLOT(j - 1), pa0, pa1, pa2, pa3); exp_half(pB0);
;             ENDI();
;             STAGE(j + 2);
;             SBAR(); BIAS(pA0, pA1, j + 1); qkt<4>(pA0, pA1, K_lds + SLOT(j + 1), qr, r32p, hip, colB0);
;             exp_half(pB1); pack_p(pB0, pB1, l_reg, pa0, pa1, pa2, pa3); SBAR();
;             pv_d0(o, vb0 + SLOT(j), pa0, pa1, pa2, pa3); exp_half(pA0);
;             ENDI();
;         }
	v_mfma_f32_32x32x16_bf16 v[0:15], v[128:131], v[156:159], v[0:15]
	ds_read_b64_tr_b16 v[156:157], v184 offset:5632
	ds_read_b64_tr_b16 v[158:159], v184 offset:7680
	v_exp_f32_e32 v94, v94
	v_exp_f32_e32 v95, v95
	v_add_f32_e32 v182, v92, v182
	v_add_f32_e32 v182, v93, v182
	v_cvt_pk_bf16_f32 v134, v92, v93
	v_add_f32_e32 v182, v94, v182
	v_add_f32_e32 v182, v95, v182
	v_cvt_pk_bf16_f32 v135, v94, v95
	v_mfma_f32_32x32x16_bf16 v[112:127], v[192:195], v[172:175], v[112:127]
	v_mfma_f32_32x32x16_bf16 v[96:111], v[196:199], v[172:175], v[96:111]
	v_mfma_f32_32x32x16_bf16 v[112:127], v[200:203], v[168:171], v[112:127]
	v_mfma_f32_32x32x16_bf16 v[96:111], v[204:207], v[168:171], v[96:111]
	s_waitcnt lgkmcnt(6)
	v_mfma_f32_32x32x16_bf16 v[48:63], v[132:135], v[144:147], v[48:63]
	ds_read_b64_tr_b16 v[144:145], v184 offset:8192
	ds_read_b64_tr_b16 v[146:147], v184 offset:10240
	v_exp_f32_e32 v64, v64
	v_exp_f32_e32 v65, v65
	s_waitcnt lgkmcnt(6)
	v_mfma_f32_32x32x16_bf16 v[32:47], v[132:135], v[148:151], v[32:47]
	ds_read_b64_tr_b16 v[148:149], v184 offset:8704
	ds_read_b64_tr_b16 v[150:151], v184 offset:10752
	v_exp_f32_e32 v66, v66
	v_exp_f32_e32 v67, v67
	v_add_f32_e32 v182, v64, v182
	v_add_f32_e32 v182, v65, v182
	v_cvt_pk_bf16_f32 v136, v64, v65
	s_waitcnt lgkmcnt(6)
	v_mfma_f32_32x32x16_bf16 v[16:31], v[132:135], v[152:155], v[16:31]
	ds_read_b64_tr_b16 v[152:153], v184 offset:9216
	ds_read_b64_tr_b16 v[154:155], v184 offset:11264
	v_exp_f32_e32 v68, v68
	v_exp_f32_e32 v69, v69
	v_add_f32_e32 v182, v66, v182
	v_add_f32_e32 v182, v67, v182
	v_cvt_pk_bf16_f32 v137, v66, v67
	s_waitcnt lgkmcnt(6)
	v_mfma_f32_32x32x16_bf16 v[0:15], v[132:135], v[156:159], v[0:15]
	ds_read_b64_tr_b16 v[156:157], v184 offset:9728
	ds_read_b64_tr_b16 v[158:159], v184 offset:11776
	v_exp_f32_e32 v70, v70
	v_exp_f32_e32 v71, v71
	v_add_f32_e32 v182, v68, v182
	v_add_f32_e32 v182, v69, v182
	v_cvt_pk_bf16_f32 v138, v68, v69
	v_add_f32_e32 v182, v70, v182
	v_add_f32_e32 v182, v71, v182
	v_cvt_pk_bf16_f32 v139, v70, v71
	v_mfma_f32_32x32x16_bf16 v[112:127], v[208:211], v[164:167], v[112:127]
	v_mfma_f32_32x32x16_bf16 v[96:111], v[212:215], v[164:167], v[96:111]
	v_mfma_f32_32x32x16_bf16 v[112:127], v[216:219], v[160:163], v[112:127]
	v_mfma_f32_32x32x16_bf16 v[96:111], v[220:223], v[160:163], v[96:111]
	s_waitcnt lgkmcnt(6)
	v_mfma_f32_32x32x16_bf16 v[48:63], v[136:139], v[144:147], v[48:63]
	ds_read_b64_tr_b16 v[144:145], v184 offset:12288
	ds_read_b64_tr_b16 v[146:147], v184 offset:14336
	v_exp_f32_e32 v72, v72
	v_exp_f32_e32 v73, v73
	s_waitcnt lgkmcnt(6)
	v_mfma_f32_32x32x16_bf16 v[32:47], v[136:139], v[148:151], v[32:47]
	ds_read_b64_tr_b16 v[148:149], v184 offset:12800
	ds_read_b64_tr_b16 v[150:151], v184 offset:14848
	v_exp_f32_e32 v74, v74
	v_exp_f32_e32 v75, v75
	v_add_f32_e32 v182, v72, v182
	v_add_f32_e32 v182, v73, v182
	v_cvt_pk_bf16_f32 v140, v72, v73
	s_waitcnt lgkmcnt(6)
	v_mfma_f32_32x32x16_bf16 v[16:31], v[136:139], v[152:155], v[16:31]
	ds_read_b64_tr_b16 v[152:153], v184 offset:13312
	ds_read_b64_tr_b16 v[154:155], v184 offset:15360
	v_exp_f32_e32 v76, v76
	v_exp_f32_e32 v77, v77
	v_add_f32_e32 v182, v74, v182
	v_add_f32_e32 v182, v75, v182
	v_cvt_pk_bf16_f32 v141, v74, v75
	s_waitcnt lgkmcnt(6)
	v_mfma_f32_32x32x16_bf16 v[0:15], v[136:139], v[156:159], v[0:15]
	ds_read_b64_tr_b16 v[156:157], v184 offset:13824
	ds_read_b64_tr_b16 v[158:159], v184 offset:15872
	v_exp_f32_e32 v78, v78
	v_exp_f32_e32 v79, v79
	v_add_f32_e32 v182, v76, v182
	v_add_f32_e32 v182, v77, v182
	v_cvt_pk_bf16_f32 v142, v76, v77
	v_add_f32_e32 v182, v78, v182
	v_add_f32_e32 v182, v79, v182
	v_cvt_pk_bf16_f32 v143, v78, v79
	s_nop 1
	s_waitcnt lgkmcnt(6)
	v_mfma_f32_32x32x16_bf16 v[48:63], v[140:143], v[144:147], v[48:63]
	v_exp_f32_e32 v112, v112
	v_exp_f32_e32 v113, v113
	s_waitcnt lgkmcnt(4)
	v_mfma_f32_32x32x16_bf16 v[32:47], v[140:143], v[148:151], v[32:47]
	v_exp_f32_e32 v114, v114
	v_exp_f32_e32 v115, v115
	v_add_f32_e32 v182, v112, v182
	v_add_f32_e32 v182, v113, v182
	v_cvt_pk_bf16_f32 v128, v112, v113
	s_waitcnt lgkmcnt(2)
	v_mfma_f32_32x32x16_bf16 v[16:31], v[140:143], v[152:155], v[16:31]
	v_exp_f32_e32 v116, v116
	v_exp_f32_e32 v117, v117
	v_add_f32_e32 v182, v114, v182
	v_add_f32_e32 v182, v115, v182
	v_cvt_pk_bf16_f32 v129, v114, v115
	s_waitcnt lgkmcnt(0)
	v_mfma_f32_32x32x16_bf16 v[0:15], v[140:143], v[156:159], v[0:15]
	v_exp_f32_e32 v118, v118
	v_exp_f32_e32 v119, v119
	v_add_f32_e32 v182, v116, v182
	v_add_f32_e32 v182, v117, v182
	v_cvt_pk_bf16_f32 v130, v116, v117
	v_add_f32_e32 v182, v118, v182
	v_add_f32_e32 v182, v119, v182
	v_cvt_pk_bf16_f32 v131, v118, v119
	s_nop 1
	s_add_i32 s54, s54, 1
	s_add_i32 s55, s55, 0x4000
	s_and_b32 s55, s55, 0xc000
	s_cmp_ge_i32 s54, s62
	s_cbranch_scc1 .Lsym_last
	s_waitcnt vmcnt(0)
	s_barrier
	s_add_i32 s53, s55, 0x4000
	s_and_b32 s53, s53, 0xc000
	s_add_i32 s53, s53, 0x10000
	v_add_u32_e32 v196, s53, v178
	ds_read_b128 v[192:195], v196
	ds_read_b128 v[196:199], v196 offset:8192
	v_add_u32_e32 v204, s53, v179
	ds_read_b128 v[200:203], v204
	ds_read_b128 v[204:207], v204 offset:8192
	v_add_u32_e32 v212, s53, v180
	ds_read_b128 v[208:211], v212
	ds_read_b128 v[212:215], v212 offset:8192
	v_add_u32_e32 v220, s53, v181
	ds_read_b128 v[216:219], v220
	ds_read_b128 v[220:223], v220 offset:8192
	s_add_i32 s53, s54, 2
	s_cmp_le_i32 s53, s62
	s_cbranch_scc0 .Lsym_nostage_o
	s_add_i32 s53, s25, s58
	s_mov_b32 m0, s53
	s_add_u32 s60, s56, 0x70000
	s_addc_u32 s61, s57, 0
	global_load_lds_dwordx4 v176, s[56:57]
	s_add_i32 m0, s53, 0x2000
	s_nop 0
	global_load_lds_dwordx4 v176, s[60:61]
	s_add_i32 s53, s24, s58
	s_mov_b32 m0, s53
	s_nop 0
	global_load_lds_dwordx4 v188, s[56:57]
	s_add_i32 m0, s53, 0x2000
	s_nop 0
	global_load_lds_dwordx4 v188, s[60:61]
	s_add_u32 s56, s56, 0xe0000
	s_addc_u32 s57, s57, 0
	s_add_i32 s58, s58, 0x4000
	s_and_b32 s58, s58, 0xc000
; template <int KS> __device__ __forceinline__ void pv_ks(f32x16* o, int vb, bf16x8 pa) {
;     const s16x4 l0 = tr_read<v_rd_off(0, KS, 0)>(vb), h0 = tr_read<v_rd_off(0, KS, 1)>(vb), l1 = tr_read<v_rd_off(1, KS, 0)>(vb), h1 = tr_read<v_rd_off(1, KS, 1)>(vb);
;     const s16x4 l2 = tr_read<v_rd_off(2, KS, 0)>(vb), h2 = tr_read<v_rd_off(2, KS, 1)>(vb), l3 = tr_read<v_rd_off(3, KS, 0)>(vb), h3 = tr_read<v_rd_off(3, KS, 1)>(vb);
;     ...
;     asm volatile("s_waitcnt lgkmcnt(6)" ::: "memory"); SBAR();
;     o[0] = __builtin_amdgcn_mfma_f32_32x32x16_bf16(pa, PK(l0, h0), o[0], 0, 0, 0);
;     asm volatile("s_waitcnt lgkmcnt(4)" ::: "memory"); SBAR();
;     o[1] = __builtin_amdgcn_mfma_f32_32x32x16_bf16(pa, PK(l1, h1), o[1], 0, 0, 0);
;     asm volatile("s_waitcnt lgkmcnt(2)" ::: "memory"); SBAR();
;     o[2] = __builtin_amdgcn_mfma_f32_32x32x16_bf16(pa, PK(l2, h2), o[2], 0, 0, 0);
;     asm volatile("s_waitcnt lgkmcnt(0)" ::: "memory"); SBAR();
;     o[3] = __builtin_amdgcn_mfma_f32_32x32x16_bf16(pa, PK(l3, h3), o[3], 0, 0, 0);
;     ...
; }
; __device__ __forceinline__ void pv_d0(f32x16* o, int vb, bf16x8 pa0, bf16x8 pa1, bf16x8 pa2, bf16x8 pa3) {
;     __builtin_amdgcn_s_setprio(1);
;     pv_ks<0>(o, vb, pa0); pv_ks<1>(o, vb, pa1); pv_ks<2>(o, vb, pa2); pv_ks<3>(o, vb, pa3);
;     __builtin_amdgcn_s_setprio(0);
; }
; __device__ __forceinline__ void exp_half(f32x16& p) {
; #pragma unroll
;     for (int r = 0; r < 16; ++r) p[r] = __builtin_amdgcn_exp2f(p[r]);
; }
; __device__ __forceinline__ void pack_p(const f32x16& p0, const f32x16& p1, float& l_reg, bf16x8& pa0, bf16x8& pa1, bf16x8& pa2, bf16x8& pa3) {
;     float ps = 0;
; #pragma unroll
;     for (int r = 0; r < 16; ++r) ps += p0[r];
; #pragma unroll
; __device__ __forceinline__ void bias_init(f32x16& p0, f32x16& p1, float base, float nslope2, float nM2, int rel  ) {
;     if (rel <= -63 || rel >= 31) {
;         const float sg = (rel < 0) ? -nslope2 : nslope2, lbv = fmaf(-sg, base, nM2);
; #pragma unroll
;         for (int r = 0; r < 16; ++r) { p0[r] = fmaf((float)((r & 3) + 8 * (r >> 2)), sg, lbv); p1[r] = fmaf((float)((r & 3) + 8 * (r >> 2) + 32), sg, lbv); }
;     } else {
; #pragma unroll
;         for (int r = 0; r < 16; ++r) { const float d = base - (float)((r & 3) + 8 * (r >> 2));
;             p0[r] = fmaf(fabsf(d), nslope2, nM2); p1[r] = fmaf(fabsf(d - 32.f), nslope2, nM2); }
;     }
; }
.Lsym_nostage_o:
	s_add_i32 s53, s54, 1
	s_lshl_b32 s53, s53, 6
	v_subrev_u32_e32 v183, s53, v236
	v_cvt_f32_i32_e32 v183, v183
	s_add_i32 s53, s53, s63
	s_add_i32 s100, s53, 62
	s_cmp_lt_u32 s100, 93
	s_cbranch_scc1 .Lsym_diag_o
	s_cmp_lt_i32 s53, 0
	s_cselect_b32 s100, -1.0, 1.0
	v_mul_f32_e32 v185, s100, v186
	v_fma_f32 v187, -v185, v183, s16
	v_fmamk_f32 v80, v185, 0x00000000, v187
	v_fmamk_f32 v64, v185, 0x42000000, v187
	v_fmamk_f32 v81, v185, 0x3f800000, v187
	v_fmamk_f32 v65, v185, 0x42040000, v187
	v_fmamk_f32 v82, v185, 0x40000000, v187
	v_fmamk_f32 v66, v185, 0x42080000, v187
	v_fmamk_f32 v83, v185, 0x40400000, v187
	v_fmamk_f32 v67, v185, 0x420c0000, v187
	v_fmamk_f32 v84, v185, 0x41000000, v187
	v_fmamk_f32 v68, v185, 0x42200000, v187
	v_fmamk_f32 v85, v185, 0x41100000, v187
	v_fmamk_f32 v69, v185, 0x42240000, v187
	v_fmamk_f32 v86, v185, 0x41200000, v187
	v_fmamk_f32 v70, v185, 0x42280000, v187
	v_fmamk_f32 v87, v185, 0x41300000, v187
	v_fmamk_f32 v71, v185, 0x422c0000, v187
	v_fmamk_f32 v88, v185, 0x41800000, v187
	v_fmamk_f32 v72, v185, 0x42400000, v187
	v_fmamk_f32 v89, v185, 0x41880000, v187
	v_fmamk_f32 v73, v185, 0x42440000, v187
	v_fmamk_f32 v90, v185, 0x41900000, v187
	v_fmamk_f32 v74, v185, 0x42480000, v187
	v_fmamk_f32 v91, v185, 0x41980000, v187
	v_fmamk_f32 v75, v185, 0x424c0000, v187
	v_fmamk_f32 v92, v185, 0x41c00000, v187
	v_fmamk_f32 v76, v185, 0x42600000, v187
	v_fmamk_f32 v93, v185, 0x41c80000, v187
	v_fmamk_f32 v77, v185, 0x42640000, v187
	v_fmamk_f32 v94, v185, 0x41d00000, v187
	v_fmamk_f32 v78, v185, 0x42680000, v187
	v_fmamk_f32 v95, v185, 0x41d80000, v187
	v_fmamk_f32 v79, v185, 0x426c0000, v187
	s_branch .Lsym_biasdone_o
.Lsym_diag_o:
	v_add_f32_e32 v190, 0x00000000, v183
	v_add_f32_e32 v191, 0xc2000000, v183
	v_fma_f32 v80, |v190|, v186, s16
	v_fma_f32 v64, |v191|, v186, s16
	v_add_f32_e32 v190, 0xbf800000, v183
	v_add_f32_e32 v191, 0xc2040000, v183
	v_fma_f32 v81, |v190|, v186, s16
	v_fma_f32 v65, |v191|, v186, s16
	v_add_f32_e32 v190, 0xc0000000, v183
	v_add_f32_e32 v191, 0xc2080000, v183
	v_fma_f32 v82, |v190|, v186, s16
	v_fma_f32 v66, |v191|, v186, s16
	v_add_f32_e32 v190, 0xc0400000, v183
	v_add_f32_e32 v191, 0xc20c0000, v183
	v_fma_f32 v83, |v190|, v186, s16
	v_fma_f32 v67, |v191|, v186, s16
	v_add_f32_e32 v190, 0xc1000000, v183
	v_add_f32_e32 v191, 0xc2200000, v183
	v_fma_f32 v84, |v190|, v186, s16
	v_fma_f32 v68, |v191|, v186, s16
	v_add_f32_e32 v190, 0xc1100000, v183
	v_add_f32_e32 v191, 0xc2240000, v183
	v_fma_f32 v85, |v190|, v186, s16
	v_fma_f32 v69, |v191|, v186, s16
	v_add_f32_e32 v190, 0xc1200000, v183
	v_add_f32_e32 v191, 0xc2280000, v183
	v_fma_f32 v86, |v190|, v186, s16
	v_fma_f32 v70, |v191|, v186, s16
	v_add_f32_e32 v190, 0xc1300000, v183
	v_add_f32_e32 v191, 0xc22c0000, v183
	v_fma_f32 v87, |v190|, v186, s16
	v_fma_f32 v71, |v191|, v186, s16
	v_add_f32_e32 v190, 0xc1800000, v183
	v_add_f32_e32 v191, 0xc2400000, v183
	v_fma_f32 v88, |v190|, v186, s16
	v_fma_f32 v72, |v191|, v186, s16
	v_add_f32_e32 v190, 0xc1880000, v183
	v_add_f32_e32 v191, 0xc2440000, v183
	v_fma_f32 v89, |v190|, v186, s16
	v_fma_f32 v73, |v191|, v186, s16
	v_add_f32_e32 v190, 0xc1900000, v183
	v_add_f32_e32 v191, 0xc2480000, v183
	v_fma_f32 v90, |v190|, v186, s16
	v_fma_f32 v74, |v191|, v186, s16
	v_add_f32_e32 v190, 0xc1980000, v183
	v_add_f32_e32 v191, 0xc24c0000, v183
	v_fma_f32 v91, |v190|, v186, s16
	v_fma_f32 v75, |v191|, v186, s16
	v_add_f32_e32 v190, 0xc1c00000, v183
	v_add_f32_e32 v191, 0xc2600000, v183
	v_fma_f32 v92, |v190|, v186, s16
	v_fma_f32 v76, |v191|, v186, s16
	v_add_f32_e32 v190, 0xc1c80000, v183
	v_add_f32_e32 v191, 0xc2640000, v183
	v_fma_f32 v93, |v190|, v186, s16
	v_fma_f32 v77, |v191|, v186, s16
	v_add_f32_e32 v190, 0xc1d00000, v183
	v_add_f32_e32 v191, 0xc2680000, v183
	v_fma_f32 v94, |v190|, v186, s16
	v_fma_f32 v78, |v191|, v186, s16
	v_add_f32_e32 v190, 0xc1d80000, v183
	v_add_f32_e32 v191, 0xc26c0000, v183
	v_fma_f32 v95, |v190|, v186, s16
	v_fma_f32 v79, |v191|, v186, s16
.Lsym_biasdone_o:
	v_add_u32_e32 v184, s55, v252
	ds_read_b64_tr_b16 v[144:145], v184 offset:0
	ds_read_b64_tr_b16 v[146:147], v184 offset:2048
	ds_read_b64_tr_b16 v[148:149], v184 offset:512
	ds_read_b64_tr_b16 v[150:151], v184 offset:2560
	ds_read_b64_tr_b16 v[152:153], v184 offset:1024
	ds_read_b64_tr_b16 v[154:155], v184 offset:3072
	ds_read_b64_tr_b16 v[156:157], v184 offset:1536
	ds_read_b64_tr_b16 v[158:159], v184 offset:3584
	s_waitcnt lgkmcnt(6)
	v_mfma_f32_32x32x16_bf16 v[48:63], v[128:131], v[144:147], v[48:63]
	ds_read_b64_tr_b16 v[144:145], v184 offset:4096
	ds_read_b64_tr_b16 v[146:147], v184 offset:6144
	v_exp_f32_e32 v120, v120
	v_exp_f32_e32 v121, v121
	s_waitcnt lgkmcnt(6)
	v_mfma_f32_32x32x16_bf16 v[32:47], v[128:131], v[148:151], v[32:47]
	ds_read_b64_tr_b16 v[148:149], v184 offset:4608
	ds_read_b64_tr_b16 v[150:151], v184 offset:6656
	v_exp_f32_e32 v122, v122
	v_exp_f32_e32 v123, v123
	v_add_f32_e32 v182, v120, v182
	v_add_f32_e32 v182, v121, v182
	v_cvt_pk_bf16_f32 v132, v120, v121
	s_waitcnt lgkmcnt(6)
	v_mfma_f32_32x32x16_bf16 v[16:31], v[128:131], v[152:155], v[16:31]
	ds_read_b64_tr_b16 v[152:153], v184 offset:5120
	ds_read_b64_tr_b16 v[154:155], v184 offset:7168
	v_exp_f32_e32 v124, v124
	v_exp_f32_e32 v125, v125
	v_add_f32_e32 v182, v122, v182
	v_add_f32_e32 v182, v123, v182
	v_cvt_pk_bf16_f32 v133, v122, v123
	s_waitcnt lgkmcnt(6)
; template <int KS> __device__ __forceinline__ void pv_ks(f32x16* o, int vb, bf16x8 pa) {
;     const s16x4 l0 = tr_read<v_rd_off(0, KS, 0)>(vb), h0 = tr_read<v_rd_off(0, KS, 1)>(vb), l1 = tr_read<v_rd_off(1, KS, 0)>(vb), h1 = tr_read<v_rd_off(1, KS, 1)>(vb);
;     const s16x4 l2 = tr_read<v_rd_off(2, KS, 0)>(vb), h2 = tr_read<v_rd_off(2, KS, 1)>(vb), l3 = tr_read<v_rd_off(3, KS, 0)>(vb), h3 = tr_read<v_rd_off(3, KS, 1)>(vb);
;     ...
;     asm volatile("s_waitcnt lgkmcnt(6)" ::: "memory"); SBAR();
;     o[0] = __builtin_amdgcn_mfma_f32_32x32x16_bf16(pa, PK(l0, h0), o[0], 0, 0, 0);
;     asm volatile("s_waitcnt lgkmcnt(4)" ::: "memory"); SBAR();
;     o[1] = __builtin_amdgcn_mfma_f32_32x32x16_bf16(pa, PK(l1, h1), o[1], 0, 0, 0);
;     asm volatile("s_waitcnt lgkmcnt(2)" ::: "memory"); SBAR();
;     o[2] = __builtin_amdgcn_mfma_f32_32x32x16_bf16(pa, PK(l2, h2), o[2], 0, 0, 0);
;     asm volatile("s_waitcnt lgkmcnt(0)" ::: "memory"); SBAR();
;     o[3] = __builtin_amdgcn_mfma_f32_32x32x16_bf16(pa, PK(l3, h3), o[3], 0, 0, 0);
;     ...
; }
; __device__ __forceinline__ void pv_d0(f32x16* o, int vb, bf16x8 pa0, bf16x8 pa1, bf16x8 pa2, bf16x8 pa3) {
;     __builtin_amdgcn_s_setprio(1);
;     pv_ks<0>(o, vb, pa0); pv_ks<1>(o, vb, pa1); pv_ks<2>(o, vb, pa2); pv_ks<3>(o, vb, pa3);
;     __builtin_amdgcn_s_setprio(0);
; }
; __device__ __forceinline__ void exp_half(f32x16& p) {
; #pragma unroll
;     for (int r = 0; r < 16; ++r) p[r] = __builtin_amdgcn_exp2f(p[r]);
; }
; __device__ __forceinline__ void pack_p(const f32x16& p0, const f32x16& p1, float& l_reg, bf16x8& pa0, bf16x8& pa1, bf16x8& pa2, bf16x8& pa3) {
;     float ps = 0;
; #pragma unroll
;     for (int r = 0; r < 16; ++r) ps += p0[r];
; #pragma unroll
;     for (int r = 0; r < 16; ++r) ps += p1[r];
;     l_reg += ps;
;     ...
;     PK4(p0, 0, pa0); PK4(p0, 8, pa1); PK4(p1, 0, pa2); PK4(p1, 8, pa3);
;     ...
; }
; template <int ND0> __device__ __forceinline__ void qkt(f32x16& p0, f32x16& p1, const char* Ks, const bf16x8* qr, int r32, int hi, int colB0) {
; #pragma unroll
;     for (int d0 = 0; d0 < ND0; ++d0) { const int cb = colB0 + (d0 * 16 + hi * 8) * 2;
;         const bf16x8 b0 = *reinterpret_cast<const bf16x8*>(Ks + KSWZ(r32, cb));
;         const bf16x8 b1 = *reinterpret_cast<const bf16x8*>(Ks + KSWZ(32 + r32, cb));
;         p0 = __builtin_amdgcn_mfma_f32_32x32x16_bf16(b0, qr[d0], p0, 0, 0, 0);
	v_mfma_f32_32x32x16_bf16 v[0:15], v[128:131], v[156:159], v[0:15]
	ds_read_b64_tr_b16 v[156:157], v184 offset:5632
	ds_read_b64_tr_b16 v[158:159], v184 offset:7680
	v_exp_f32_e32 v126, v126
	v_exp_f32_e32 v127, v127
	v_add_f32_e32 v182, v124, v182
	v_add_f32_e32 v182, v125, v182
	v_cvt_pk_bf16_f32 v134, v124, v125
	v_add_f32_e32 v182, v126, v182
	v_add_f32_e32 v182, v127, v182
	v_cvt_pk_bf16_f32 v135, v126, v127
	v_mfma_f32_32x32x16_bf16 v[80:95], v[192:195], v[172:175], v[80:95]
	v_mfma_f32_32x32x16_bf16 v[64:79], v[196:199], v[172:175], v[64:79]
	v_mfma_f32_32x32x16_bf16 v[80:95], v[200:203], v[168:171], v[80:95]
	v_mfma_f32_32x32x16_bf16 v[64:79], v[204:207], v[168:171], v[64:79]
	s_waitcnt lgkmcnt(6)
	v_mfma_f32_32x32x16_bf16 v[48:63], v[132:135], v[144:147], v[48:63]
	ds_read_b64_tr_b16 v[144:145], v184 offset:8192
	ds_read_b64_tr_b16 v[146:147], v184 offset:10240
	v_exp_f32_e32 v96, v96
	v_exp_f32_e32 v97, v97
	s_waitcnt lgkmcnt(6)
	v_mfma_f32_32x32x16_bf16 v[32:47], v[132:135], v[148:151], v[32:47]
	ds_read_b64_tr_b16 v[148:149], v184 offset:8704
	ds_read_b64_tr_b16 v[150:151], v184 offset:10752
	v_exp_f32_e32 v98, v98
	v_exp_f32_e32 v99, v99
	v_add_f32_e32 v182, v96, v182
	v_add_f32_e32 v182, v97, v182
	v_cvt_pk_bf16_f32 v136, v96, v97
	s_waitcnt lgkmcnt(6)
	v_mfma_f32_32x32x16_bf16 v[16:31], v[132:135], v[152:155], v[16:31]
	ds_read_b64_tr_b16 v[152:153], v184 offset:9216
	ds_read_b64_tr_b16 v[154:155], v184 offset:11264
	v_exp_f32_e32 v100, v100
	v_exp_f32_e32 v101, v101
	v_add_f32_e32 v182, v98, v182
	v_add_f32_e32 v182, v99, v182
	v_cvt_pk_bf16_f32 v137, v98, v99
	s_waitcnt lgkmcnt(6)
	v_mfma_f32_32x32x16_bf16 v[0:15], v[132:135], v[156:159], v[0:15]
	ds_read_b64_tr_b16 v[156:157], v184 offset:9728
	ds_read_b64_tr_b16 v[158:159], v184 offset:11776
	v_exp_f32_e32 v102, v102
	v_exp_f32_e32 v103, v103
	v_add_f32_e32 v182, v100, v182
	v_add_f32_e32 v182, v101, v182
	v_cvt_pk_bf16_f32 v138, v100, v101
	v_add_f32_e32 v182, v102, v182
	v_add_f32_e32 v182, v103, v182
	v_cvt_pk_bf16_f32 v139, v102, v103
	v_mfma_f32_32x32x16_bf16 v[80:95], v[208:211], v[164:167], v[80:95]
	v_mfma_f32_32x32x16_bf16 v[64:79], v[212:215], v[164:167], v[64:79]
	v_mfma_f32_32x32x16_bf16 v[80:95], v[216:219], v[160:163], v[80:95]
	v_mfma_f32_32x32x16_bf16 v[64:79], v[220:223], v[160:163], v[64:79]
	s_waitcnt lgkmcnt(6)
	v_mfma_f32_32x32x16_bf16 v[48:63], v[136:139], v[144:147], v[48:63]
	ds_read_b64_tr_b16 v[144:145], v184 offset:12288
	ds_read_b64_tr_b16 v[146:147], v184 offset:14336
	v_exp_f32_e32 v104, v104
	v_exp_f32_e32 v105, v105
	s_waitcnt lgkmcnt(6)
	v_mfma_f32_32x32x16_bf16 v[32:47], v[136:139], v[148:151], v[32:47]
	ds_read_b64_tr_b16 v[148:149], v184 offset:12800
	ds_read_b64_tr_b16 v[150:151], v184 offset:14848
	v_exp_f32_e32 v106, v106
	v_exp_f32_e32 v107, v107
	v_add_f32_e32 v182, v104, v182
	v_add_f32_e32 v182, v105, v182
	v_cvt_pk_bf16_f32 v140, v104, v105
	s_waitcnt lgkmcnt(6)
	v_mfma_f32_32x32x16_bf16 v[16:31], v[136:139], v[152:155], v[16:31]
	ds_read_b64_tr_b16 v[152:153], v184 offset:13312
	ds_read_b64_tr_b16 v[154:155], v184 offset:15360
	v_exp_f32_e32 v108, v108
	v_exp_f32_e32 v109, v109
	v_add_f32_e32 v182, v106, v182
	v_add_f32_e32 v182, v107, v182
	v_cvt_pk_bf16_f32 v141, v106, v107
	s_waitcnt lgkmcnt(6)
	v_mfma_f32_32x32x16_bf16 v[0:15], v[136:139], v[156:159], v[0:15]
	ds_read_b64_tr_b16 v[156:157], v184 offset:13824
	ds_read_b64_tr_b16 v[158:159], v184 offset:15872
	v_exp_f32_e32 v110, v110
	v_exp_f32_e32 v111, v111
	v_add_f32_e32 v182, v108, v182
	v_add_f32_e32 v182, v109, v182
	v_cvt_pk_bf16_f32 v142, v108, v109
	v_add_f32_e32 v182, v110, v182
	v_add_f32_e32 v182, v111, v182
	v_cvt_pk_bf16_f32 v143, v110, v111
	s_nop 1
	s_waitcnt lgkmcnt(6)
	v_mfma_f32_32x32x16_bf16 v[48:63], v[140:143], v[144:147], v[48:63]
	v_exp_f32_e32 v80, v80
	v_exp_f32_e32 v81, v81
	s_waitcnt lgkmcnt(4)
	v_mfma_f32_32x32x16_bf16 v[32:47], v[140:143], v[148:151], v[32:47]
	v_exp_f32_e32 v82, v82
	v_exp_f32_e32 v83, v83
	v_add_f32_e32 v182, v80, v182
	v_add_f32_e32 v182, v81, v182
	v_cvt_pk_bf16_f32 v128, v80, v81
	s_waitcnt lgkmcnt(2)
	v_mfma_f32_32x32x16_bf16 v[16:31], v[140:143], v[152:155], v[16:31]
	v_exp_f32_e32 v84, v84
	v_exp_f32_e32 v85, v85
	v_add_f32_e32 v182, v82, v182
	v_add_f32_e32 v182, v83, v182
	v_cvt_pk_bf16_f32 v129, v82, v83
	s_waitcnt lgkmcnt(0)
	v_mfma_f32_32x32x16_bf16 v[0:15], v[140:143], v[156:159], v[0:15]
	v_exp_f32_e32 v86, v86
	v_exp_f32_e32 v87, v87
	v_add_f32_e32 v182, v84, v182
	v_add_f32_e32 v182, v85, v182
	v_cvt_pk_bf16_f32 v130, v84, v85
	v_add_f32_e32 v182, v86, v182
	v_add_f32_e32 v182, v87, v182
	v_cvt_pk_bf16_f32 v131, v86, v87
	s_nop 1
	s_add_i32 s54, s54, 1
	s_add_i32 s55, s55, 0x4000
	s_and_b32 s55, s55, 0xc000
	s_branch .Lsym_loop
; #define SBAR() __builtin_amdgcn_sched_barrier(0)
; template <int KS> __device__ __forceinline__ void pv_ks(f32x16* o, int vb, bf16x8 pa) {
;     const s16x4 l0 = tr_read<v_rd_off(0, KS, 0)>(vb), h0 = tr_read<v_rd_off(0, KS, 1)>(vb), l1 = tr_read<v_rd_off(1, KS, 0)>(vb), h1 = tr_read<v_rd_off(1, KS, 1)>(vb);
;     const s16x4 l2 = tr_read<v_rd_off(2, KS, 0)>(vb), h2 = tr_read<v_rd_off(2, KS, 1)>(vb), l3 = tr_read<v_rd_off(3, KS, 0)>(vb), h3 = tr_read<v_rd_off(3, KS, 1)>(vb);
;     ...
;     asm volatile("s_waitcnt lgkmcnt(6)" ::: "memory"); SBAR();
;     o[0] = __builtin_amdgcn_mfma_f32_32x32x16_bf16(pa, PK(l0, h0), o[0], 0, 0, 0);
;     asm volatile("s_waitcnt lgkmcnt(4)" ::: "memory"); SBAR();
;     o[1] = __builtin_amdgcn_mfma_f32_32x32x16_bf16(pa, PK(l1, h1), o[1], 0, 0, 0);
;     asm volatile("s_waitcnt lgkmcnt(2)" ::: "memory"); SBAR();
;     o[2] = __builtin_amdgcn_mfma_f32_32x32x16_bf16(pa, PK(l2, h2), o[2], 0, 0, 0);
;     asm volatile("s_waitcnt lgkmcnt(0)" ::: "memory"); SBAR();
;     o[3] = __builtin_amdgcn_mfma_f32_32x32x16_bf16(pa, PK(l3, h3), o[3], 0, 0, 0);
;     ...
; }
; __device__ __forceinline__ void pv_d0(f32x16* o, int vb, bf16x8 pa0, bf16x8 pa1, bf16x8 pa2, bf16x8 pa3) {
;     __builtin_amdgcn_s_setprio(1);
;     pv_ks<0>(o, vb, pa0); pv_ks<1>(o, vb, pa1); pv_ks<2>(o, vb, pa2); pv_ks<3>(o, vb, pa3);
;     __builtin_amdgcn_s_setprio(0);
; }
; __device__ __forceinline__ void exp_half(f32x16& p) {
; #pragma unroll
;     for (int r = 0; r < 16; ++r) p[r] = __builtin_amdgcn_exp2f(p[r]);
; }
; __device__ __forceinline__ void pack_p(const f32x16& p0, const f32x16& p1, float& l_reg, bf16x8& pa0, bf16x8& pa1, bf16x8& pa2, bf16x8& pa3) {
;     float ps = 0;
; #pragma unroll
;     for (int r = 0; r < 16; ++r) ps += p0[r];
; #pragma unroll
;     for (int r = 0; r < 16; ++r) ps += p1[r];
;     l_reg += ps;
; __device__ __forceinline__ void diff_unit(const DiffArgs& A, int b, int h, int qb, char* lds, int wv) {
;     ...
;         { const int lt_ = opaque_tid(wv) & 63;
;           SBAR(); BIAS(pB0, pB1, NT - 1); qkt<4>(pB0, pB1, K_lds + SLOT(NT - 1), qr, lt_ & 31, lt_ >> 5, colB0); }
;         exp_half(pA1); pack_p(pA0, pA1, l_reg, pa0, pa1, pa2, pa3); SBAR();
;         pv_d0(o, vb0 + SLOT(NT - 2), pa0, pa1, pa2, pa3); exp_half(pB0);
;         exp_half(pB1); pack_p(pB0, pB1, l_reg, pa0, pa1, pa2, pa3); SBAR();
;         pv_d0(o, vb0 + SLOT(NT - 1), pa0, pa1, pa2, pa3);
.Lsym_last:
	s_waitcnt vmcnt(0)
	s_barrier
	v_add_u32_e32 v184, s55, v252
	ds_read_b64_tr_b16 v[144:145], v184 offset:0
	ds_read_b64_tr_b16 v[146:147], v184 offset:2048
	ds_read_b64_tr_b16 v[148:149], v184 offset:512
	ds_read_b64_tr_b16 v[150:151], v184 offset:2560
	ds_read_b64_tr_b16 v[152:153], v184 offset:1024
	ds_read_b64_tr_b16 v[154:155], v184 offset:3072
	ds_read_b64_tr_b16 v[156:157], v184 offset:1536
	ds_read_b64_tr_b16 v[158:159], v184 offset:3584
	s_waitcnt lgkmcnt(6)
	v_mfma_f32_32x32x16_bf16 v[48:63], v[128:131], v[144:147], v[48:63]
	ds_read_b64_tr_b16 v[144:145], v184 offset:4096
	ds_read_b64_tr_b16 v[146:147], v184 offset:6144
	v_exp_f32_e32 v120, v120
	v_exp_f32_e32 v121, v121
	s_waitcnt lgkmcnt(6)
	v_mfma_f32_32x32x16_bf16 v[32:47], v[128:131], v[148:151], v[32:47]
	ds_read_b64_tr_b16 v[148:149], v184 offset:4608
	ds_read_b64_tr_b16 v[150:151], v184 offset:6656
	v_exp_f32_e32 v122, v122
	v_exp_f32_e32 v123, v123
	v_add_f32_e32 v182, v120, v182
	v_add_f32_e32 v182, v121, v182
	v_cvt_pk_bf16_f32 v132, v120, v121
	s_waitcnt lgkmcnt(6)
	v_mfma_f32_32x32x16_bf16 v[16:31], v[128:131], v[152:155], v[16:31]
	ds_read_b64_tr_b16 v[152:153], v184 offset:5120
	ds_read_b64_tr_b16 v[154:155], v184 offset:7168
	v_exp_f32_e32 v124, v124
	v_exp_f32_e32 v125, v125
	v_add_f32_e32 v182, v122, v182
	v_add_f32_e32 v182, v123, v182
	v_cvt_pk_bf16_f32 v133, v122, v123
	s_waitcnt lgkmcnt(6)
	v_mfma_f32_32x32x16_bf16 v[0:15], v[128:131], v[156:159], v[0:15]
	ds_read_b64_tr_b16 v[156:157], v184 offset:5632
	ds_read_b64_tr_b16 v[158:159], v184 offset:7680
	v_exp_f32_e32 v126, v126
	v_exp_f32_e32 v127, v127
	v_add_f32_e32 v182, v124, v182
	v_add_f32_e32 v182, v125, v182
	v_cvt_pk_bf16_f32 v134, v124, v125
	v_add_f32_e32 v182, v126, v182
	v_add_f32_e32 v182, v127, v182
	v_cvt_pk_bf16_f32 v135, v126, v127
	s_nop 1
	s_waitcnt lgkmcnt(6)
	v_mfma_f32_32x32x16_bf16 v[48:63], v[132:135], v[144:147], v[48:63]
	ds_read_b64_tr_b16 v[144:145], v184 offset:8192
	ds_read_b64_tr_b16 v[146:147], v184 offset:10240
	v_exp_f32_e32 v96, v96
	v_exp_f32_e32 v97, v97
	s_waitcnt lgkmcnt(6)
	v_mfma_f32_32x32x16_bf16 v[32:47], v[132:135], v[148:151], v[32:47]
	ds_read_b64_tr_b16 v[148:149], v184 offset:8704
	ds_read_b64_tr_b16 v[150:151], v184 offset:10752
	v_exp_f32_e32 v98, v98
	v_exp_f32_e32 v99, v99
	v_add_f32_e32 v182, v96, v182
	v_add_f32_e32 v182, v97, v182
	v_cvt_pk_bf16_f32 v136, v96, v97
	s_waitcnt lgkmcnt(6)
	v_mfma_f32_32x32x16_bf16 v[16:31], v[132:135], v[152:155], v[16:31]
	ds_read_b64_tr_b16 v[152:153], v184 offset:9216
	ds_read_b64_tr_b16 v[154:155], v184 offset:11264
	v_exp_f32_e32 v100, v100
	v_exp_f32_e32 v101, v101
	v_add_f32_e32 v182, v98, v182
	v_add_f32_e32 v182, v99, v182
	v_cvt_pk_bf16_f32 v137, v98, v99
	s_waitcnt lgkmcnt(6)
	v_mfma_f32_32x32x16_bf16 v[0:15], v[132:135], v[156:159], v[0:15]
	ds_read_b64_tr_b16 v[156:157], v184 offset:9728
	ds_read_b64_tr_b16 v[158:159], v184 offset:11776
	v_exp_f32_e32 v102, v102
	v_exp_f32_e32 v103, v103
	v_add_f32_e32 v182, v100, v182
	v_add_f32_e32 v182, v101, v182
	v_cvt_pk_bf16_f32 v138, v100, v101
	v_add_f32_e32 v182, v102, v182
	v_add_f32_e32 v182, v103, v182
	v_cvt_pk_bf16_f32 v139, v102, v103
	s_nop 1
	s_waitcnt lgkmcnt(6)
	v_mfma_f32_32x32x16_bf16 v[48:63], v[136:139], v[144:147], v[48:63]
	ds_read_b64_tr_b16 v[144:145], v184 offset:12288
	ds_read_b64_tr_b16 v[146:147], v184 offset:14336
	v_exp_f32_e32 v104, v104
	v_exp_f32_e32 v105, v105
	s_waitcnt lgkmcnt(6)
	v_mfma_f32_32x32x16_bf16 v[32:47], v[136:139], v[148:151], v[32:47]
	ds_read_b64_tr_b16 v[148:149], v184 offset:12800
	ds_read_b64_tr_b16 v[150:151], v184 offset:14848
	v_exp_f32_e32 v106, v106
	v_exp_f32_e32 v107, v107
	v_add_f32_e32 v182, v104, v182
	v_add_f32_e32 v182, v105, v182
	v_cvt_pk_bf16_f32 v140, v104, v105
	s_waitcnt lgkmcnt(6)
	v_mfma_f32_32x32x16_bf16 v[16:31], v[136:139], v[152:155], v[16:31]
	ds_read_b64_tr_b16 v[152:153], v184 offset:13312
	ds_read_b64_tr_b16 v[154:155], v184 offset:15360
	v_exp_f32_e32 v108, v108
	v_exp_f32_e32 v109, v109
	v_add_f32_e32 v182, v106, v182
	v_add_f32_e32 v182, v107, v182
	v_cvt_pk_bf16_f32 v141, v106, v107
	s_waitcnt lgkmcnt(6)
	v_mfma_f32_32x32x16_bf16 v[0:15], v[136:139], v[156:159], v[0:15]
	ds_read_b64_tr_b16 v[156:157], v184 offset:13824
	ds_read_b64_tr_b16 v[158:159], v184 offset:15872
	v_exp_f32_e32 v110, v110
	v_exp_f32_e32 v111, v111
	v_add_f32_e32 v182, v108, v182
	v_add_f32_e32 v182, v109, v182
	v_cvt_pk_bf16_f32 v142, v108, v109
	v_add_f32_e32 v182, v110, v182
	v_add_f32_e32 v182, v111, v182
	v_cvt_pk_bf16_f32 v143, v110, v111
	s_nop 1
	s_waitcnt lgkmcnt(6)
	v_mfma_f32_32x32x16_bf16 v[48:63], v[140:143], v[144:147], v[48:63]
	s_waitcnt lgkmcnt(4)
	v_mfma_f32_32x32x16_bf16 v[32:47], v[140:143], v[148:151], v[32:47]
	s_waitcnt lgkmcnt(2)
	v_mfma_f32_32x32x16_bf16 v[16:31], v[140:143], v[152:155], v[16:31]
	s_waitcnt lgkmcnt(0)
	v_mfma_f32_32x32x16_bf16 v[0:15], v[140:143], v[156:159], v[0:15]
	s_add_i32 s54, s54, 1
	s_add_i32 s55, s55, 0x4000
	s_and_b32 s55, s55, 0xc000
	v_mov_b32_e32 v96, v182
